# GLA scan pass 1: same split of the output-row stores between the two k-half wave pairs
# speedup vs baseline: 1.1123x; 1.0019x over previous
.LBB0_1160:
	ds_read_b128 v[32:35], v139 offset:32768
	ds_read_b128 v[36:39], v139 offset:32800
	ds_read_b128 v[40:43], v139 offset:32896
	s_waitcnt lgkmcnt(2)
	v_pk_mul_f32 v[0:1], v[0:1], v[32:33]
	v_pk_mul_f32 v[2:3], v[2:3], v[34:35]
	ds_read_b128 v[32:35], v139 offset:32928
	s_waitcnt lgkmcnt(2)
	v_pk_mul_f32 v[4:5], v[4:5], v[36:37]
	v_pk_mul_f32 v[6:7], v[6:7], v[38:39]
	ds_read_b128 v[36:39], v139 offset:32960
	s_waitcnt lgkmcnt(1)
	v_pk_mul_f32 v[20:21], v[20:21], v[32:33]
	v_pk_mul_f32 v[22:23], v[22:23], v[34:35]
	ds_read_b128 v[32:35], v139 offset:32832
	v_pk_mul_f32 v[16:17], v[16:17], v[40:41]
	v_pk_mul_f32 v[18:19], v[18:19], v[42:43]
	s_waitcnt lgkmcnt(0)
	v_pk_mul_f32 v[8:9], v[8:9], v[32:33]
	v_pk_mul_f32 v[10:11], v[10:11], v[34:35]
	ds_read_b128 v[32:35], v139 offset:32864
	v_pk_mul_f32 v[24:25], v[24:25], v[36:37]
	v_pk_mul_f32 v[26:27], v[26:27], v[38:39]
	ds_read_b128 v[36:39], v139 offset:32992
	s_waitcnt lgkmcnt(1)
	v_pk_mul_f32 v[12:13], v[12:13], v[32:33]
	v_pk_mul_f32 v[14:15], v[14:15], v[34:35]
	s_waitcnt lgkmcnt(0)
	v_pk_mul_f32 v[28:29], v[28:29], v[36:37]
	v_pk_mul_f32 v[30:31], v[30:31], v[38:39]
	ds_read_b128 v[200:203], v148 offset:8704
	ds_read_b128 v[204:207], v149
	ds_read_b128 v[208:211], v149 offset:32
	ds_read_b128 v[212:215], v150 offset:8704
	ds_read_b128 v[216:219], v151 offset:8704
	ds_read_b128 v[194:197], v149 offset:64
	s_waitcnt lgkmcnt(4)
	v_mfma_f32_32x32x16_bf16 v[32:47], v[200:203], v[204:207], 0
	ds_read_b128 v[200:203], v152 offset:8704
	ds_read_b128 v[204:207], v149 offset:96
	s_waitcnt lgkmcnt(4)
	v_mfma_f32_32x32x16_bf16 v[32:47], v[212:215], v[208:211], v[32:47]
	ds_read_b128 v[208:211], v153 offset:8704
	ds_read_b128 v[212:215], v149 offset:128
	s_waitcnt lgkmcnt(4)
	v_mfma_f32_32x32x16_bf16 v[32:47], v[216:219], v[194:197], v[32:47]
	ds_read_b128 v[216:219], v154 offset:8704
	ds_read_b128 v[194:197], v149 offset:160
	s_waitcnt lgkmcnt(4)
	v_mfma_f32_32x32x16_bf16 v[32:47], v[200:203], v[204:207], v[32:47]
	ds_read_b128 v[200:203], v155 offset:8704
	ds_read_b128 v[204:207], v149 offset:192
	s_waitcnt lgkmcnt(4)
	v_mfma_f32_32x32x16_bf16 v[32:47], v[208:211], v[212:215], v[32:47]
	ds_read_b128 v[208:211], v156 offset:8704
	ds_read_b128 v[212:215], v149 offset:224
	s_waitcnt lgkmcnt(4)
	v_mfma_f32_32x32x16_bf16 v[32:47], v[216:219], v[194:197], v[32:47]
	s_waitcnt lgkmcnt(2)
	v_mfma_f32_32x32x16_bf16 v[32:47], v[200:203], v[204:207], v[32:47]
	s_waitcnt lgkmcnt(0)
	v_mfma_f32_32x32x16_bf16 v[32:47], v[208:211], v[212:215], v[32:47]
	s_nop 11
	v_cndmask_b32_e64 v48, v32, 0, s[36:37]
	v_cndmask_b32_e64 v64, v48, v32, s[40:41]
	v_cndmask_b32_e64 v160, 0, v33, s[40:41]
	v_cndmask_b32_e64 v161, v34, 0, s[42:43]
	v_cndmask_b32_e64 v162, v35, 0, s[44:45]
	v_cndmask_b32_e64 v163, v36, 0, s[46:47]
	v_cndmask_b32_e64 v164, v37, 0, s[48:49]
	v_cndmask_b32_e64 v165, v38, 0, s[50:51]
	v_cndmask_b32_e64 v166, v39, 0, s[52:53]
	ds_read2_b64 v[32:35], v142 offset1:2
	ds_read2_b64 v[36:39], v142 offset0:4 offset1:6
	v_cndmask_b32_e64 v167, v40, 0, s[54:55]
	v_cndmask_b32_e64 v168, v41, 0, s[56:57]
	v_cndmask_b32_e64 v169, v42, 0, s[58:59]
	v_cndmask_b32_e64 v170, v43, 0, s[60:61]
	v_cvt_pk_bf16_f32 v40, v0, v1
	v_cvt_pk_bf16_f32 v41, v2, v3
	v_cvt_pk_bf16_f32 v42, v4, v5
	v_cvt_pk_bf16_f32 v43, v6, v7
	v_cndmask_b32_e64 v44, v44, 0, s[62:63]
	v_cndmask_b32_e64 v45, v45, 0, s[64:65]
	s_waitcnt lgkmcnt(1)
	v_mfma_f32_32x32x16_bf16 v[48:63], v[32:35], v[40:43], 0
	ds_read2_b64 v[32:35], v142 offset0:8 offset1:10
	v_cvt_pk_bf16_f32 v40, v16, v17
	v_cvt_pk_bf16_f32 v41, v18, v19
	v_cvt_pk_bf16_f32 v42, v20, v21
	v_cvt_pk_bf16_f32 v43, v22, v23
	v_cndmask_b32_e64 v46, v46, 0, s[66:67]
	s_waitcnt lgkmcnt(0)
	v_mfma_f32_32x32x16_bf16 v[48:63], v[32:35], v[40:43], v[48:63]
	v_cvt_pk_bf16_f32 v32, v8, v9
	v_cvt_pk_bf16_f32 v33, v10, v11
	v_cvt_pk_bf16_f32 v34, v12, v13
	v_cvt_pk_bf16_f32 v35, v14, v15
	s_nop 1
	v_mfma_f32_32x32x16_bf16 v[48:63], v[36:39], v[32:35], v[48:63]
	ds_read2_b64 v[32:35], v142 offset0:12 offset1:14
	v_cvt_pk_bf16_f32 v36, v24, v25
	v_cvt_pk_bf16_f32 v37, v26, v27
	v_cvt_pk_bf16_f32 v38, v28, v29
	v_cvt_pk_bf16_f32 v39, v30, v31
	s_waitcnt lgkmcnt(0)
	s_nop 0
	v_mfma_f32_32x32x16_bf16 v[48:63], v[32:35], v[36:39], v[48:63]
	v_cndmask_b32_e64 v32, v47, 0, s[68:69]
	v_cvt_pk_bf16_f32 v36, v64, v160
	v_cvt_pk_bf16_f32 v33, v161, v162
	v_cvt_pk_bf16_f32 v34, v163, v164
	v_cvt_pk_bf16_f32 v35, v165, v166
	v_cvt_pk_bf16_f32 v37, v167, v168
	v_cvt_pk_bf16_f32 v38, v169, v170
	v_cvt_pk_bf16_f32 v39, v44, v45
	v_cvt_pk_bf16_f32 v32, v46, v32
	v_cndmask_b32_e64 v35, v32, v35, s[70:71]
	v_cndmask_b32_e64 v34, v39, v34, s[70:71]
	v_cndmask_b32_e64 v33, v38, v33, s[70:71]
	v_cndmask_b32_e64 v32, v37, v36, s[70:71]
	ds_read_b64_tr_b16 v[36:37], v124
	ds_read_b64_tr_b16 v[38:39], v125
	s_waitcnt lgkmcnt(0)
	v_add_u32_e32 v166, 0x8000, v143
	v_add_u32_e32 v165, 0x8400, v143
	v_mfma_f32_32x32x16_bf16 v[48:63], v[32:35], v[36:39], v[48:63]
	v_add_u32_e32 v164, 0x8800, v143
	v_add_u32_e32 v163, 0x8c00, v143
	s_mov_b64 s[18:19], exec
	s_cmp_lg_u64 s[72:73], 0
	s_cbranch_scc0 .Lsov0_k0
	s_nop 7
	ds_write2_b32 v166, v48, v49 offset0:128 offset1:160
	ds_write2_b32 v166, v50, v51 offset0:192 offset1:224
	ds_write2_b32 v165, v52, v53 offset0:128 offset1:160
	ds_write2_b32 v165, v54, v55 offset0:192 offset1:224
	s_branch .LBB0_1162
.Lsov0_k0:
	s_nop 7
	ds_write2_b32 v164, v56, v57 offset0:128 offset1:160
	ds_write2_b32 v164, v58, v59 offset0:192 offset1:224
	ds_write2_b32 v163, v60, v61 offset0:128 offset1:160
	ds_write2_b32 v163, v62, v63 offset0:192 offset1:224
.LBB0_1162:
	s_or_b64 exec, exec, s[18:19]
	ds_read_b64_tr_b16 v[172:173], v126
	ds_read_b64_tr_b16 v[174:175], v127
	ds_read_b64_tr_b16 v[168:169], v128
	ds_read_b64_tr_b16 v[170:171], v129
	ds_read_b64_tr_b16 v[44:45], v130
	ds_read_b64_tr_b16 v[46:47], v131
	ds_read_b64_tr_b16 v[40:41], v132
	ds_read_b64_tr_b16 v[42:43], v133
	ds_read_b64_tr_b16 v[36:37], v120
	ds_read_b64_tr_b16 v[38:39], v121
	ds_read_b64_tr_b16 v[32:33], v122
	ds_read_b64_tr_b16 v[34:35], v123
	s_waitcnt lgkmcnt(0)
	v_add_u32_e32 v162, 0x8000, v144
	v_mfma_f32_32x32x16_bf16 v[0:15], v[172:175], v[36:39], v[0:15]
	v_add_u32_e32 v161, 0x8400, v144
	v_add_u32_e32 v160, 0x8800, v144
	v_add_u32_e32 v64, 0x8c00, v144
	s_waitcnt lgkmcnt(0)
	s_barrier
	v_mfma_f32_32x32x16_bf16 v[16:31], v[44:47], v[36:39], v[16:31]
	v_mfma_f32_32x32x16_bf16 v[0:15], v[168:171], v[32:35], v[0:15]
	v_mfma_f32_32x32x16_bf16 v[16:31], v[40:43], v[32:35], v[16:31]
	s_mov_b64 s[18:19], exec
	s_cmp_lg_u64 s[70:71], 0
	s_cbranch_scc1 .Lsot0_k0
	s_cmp_lg_u64 s[72:73], 0
	s_cbranch_scc0 .LBB0_1164
	s_sub_i32 s90, s2, 64
	s_add_i32 s91, s3, 0x60
	s_and_b64 s[20:21], s[74:75], exec
	s_cselect_b32 s20, s90, s91
	s_ashr_i32 s21, s20, 31
	s_add_u32 s20, s20, s16
	s_addc_u32 s21, s21, s24
	v_add_u32_e32 v194, 0x8800, v143
	ds_read2_b32 v[208:209], v194 offset0:128 offset1:160
	ds_read2_b32 v[210:211], v194 offset0:192 offset1:224
	v_add_u32_e32 v195, 0x8c00, v143
	ds_read2_b32 v[212:213], v195 offset0:128 offset1:160
	ds_read2_b32 v[214:215], v195 offset0:192 offset1:224
	s_waitcnt lgkmcnt(3)
	v_add_f32_e32 v218, v56, v208
	s_add_u32 s90, s20, s31
	s_addc_u32 s91, s21, s33
	s_lshl_b64 s[90:91], s[90:91], 11
	v_cvt_pk_bf16_f32 v218, v218, v218
	v_lshl_add_u64 v[216:217], v[114:115], 0, s[90:91]
	global_store_short v[216:217], v218, off
	v_add_f32_e32 v219, v57, v209
	s_add_u32 s90, s20, s34
	s_addc_u32 s91, s21, s35
	s_lshl_b64 s[90:91], s[90:91], 11
	v_cvt_pk_bf16_f32 v219, v219, v219
	v_lshl_add_u64 v[216:217], v[114:115], 0, s[90:91]
	global_store_short v[216:217], v219, off
	s_waitcnt lgkmcnt(2)
	v_add_f32_e32 v218, v58, v210
	s_add_u32 s90, s20, s38
	s_addc_u32 s91, s21, s39
	s_lshl_b64 s[90:91], s[90:91], 11
	v_cvt_pk_bf16_f32 v218, v218, v218
	v_lshl_add_u64 v[216:217], v[114:115], 0, s[90:91]
	global_store_short v[216:217], v218, off
	v_add_f32_e32 v219, v59, v211
	s_add_u32 s90, s20, s77
	s_addc_u32 s91, s21, s78
	s_lshl_b64 s[90:91], s[90:91], 11
	v_cvt_pk_bf16_f32 v219, v219, v219
	v_lshl_add_u64 v[216:217], v[114:115], 0, s[90:91]
	global_store_short v[216:217], v219, off
	s_waitcnt lgkmcnt(1)
	v_add_f32_e32 v218, v60, v212
	s_add_u32 s90, s20, s79
	s_addc_u32 s91, s21, s80
	s_lshl_b64 s[90:91], s[90:91], 11
	v_cvt_pk_bf16_f32 v218, v218, v218
	v_lshl_add_u64 v[216:217], v[114:115], 0, s[90:91]
	global_store_short v[216:217], v218, off
	v_add_f32_e32 v219, v61, v213
	s_add_u32 s90, s20, s81
	s_addc_u32 s91, s21, s82
	s_lshl_b64 s[90:91], s[90:91], 11
	v_cvt_pk_bf16_f32 v219, v219, v219
	v_lshl_add_u64 v[216:217], v[114:115], 0, s[90:91]
	global_store_short v[216:217], v219, off
	s_waitcnt lgkmcnt(0)
	v_add_f32_e32 v218, v62, v214
	s_add_u32 s90, s20, s83
	s_addc_u32 s91, s21, s84
	s_lshl_b64 s[90:91], s[90:91], 11
	v_cvt_pk_bf16_f32 v218, v218, v218
	v_lshl_add_u64 v[216:217], v[114:115], 0, s[90:91]
	global_store_short v[216:217], v218, off
	v_add_f32_e32 v219, v63, v215
	s_add_u32 s90, s20, s86
	s_addc_u32 s91, s21, s87
	s_lshl_b64 s[90:91], s[90:91], 11
	v_cvt_pk_bf16_f32 v219, v219, v219
	v_lshl_add_u64 v[216:217], v[114:115], 0, s[90:91]
	global_store_short v[216:217], v219, off
	s_branch .LBB0_1164
.Lsot0_k0:
	s_sub_i32 s90, s2, 64
	s_add_i32 s91, s3, 0x60
	s_and_b64 s[20:21], s[74:75], exec
	s_cselect_b32 s20, s90, s91
	s_ashr_i32 s21, s20, 31
	s_add_u32 s20, s20, s16
	s_addc_u32 s21, s21, s24
	ds_read2_b32 v[200:201], v162 offset0:128 offset1:160
	ds_read2_b32 v[202:203], v162 offset0:192 offset1:224
	ds_read2_b32 v[204:205], v161 offset0:128 offset1:160
	ds_read2_b32 v[206:207], v161 offset0:192 offset1:224
	s_waitcnt lgkmcnt(3)
	v_add_f32_e32 v218, v48, v200
	s_lshl_b64 s[90:91], s[20:21], 11
	v_cvt_pk_bf16_f32 v218, v218, v218
	v_lshl_add_u64 v[216:217], v[114:115], 0, s[90:91]
	global_store_short v[216:217], v218, off
	v_add_f32_e32 v219, v49, v201
	s_add_u32 s90, s20, s5
	s_addc_u32 s91, s21, s6
	s_lshl_b64 s[90:91], s[90:91], 11
	v_cvt_pk_bf16_f32 v219, v219, v219
	v_lshl_add_u64 v[216:217], v[114:115], 0, s[90:91]
	global_store_short v[216:217], v219, off
	s_waitcnt lgkmcnt(2)
	v_add_f32_e32 v218, v50, v202
	s_add_u32 s90, s20, s7
	s_addc_u32 s91, s21, s12
	s_lshl_b64 s[90:91], s[90:91], 11
	v_cvt_pk_bf16_f32 v218, v218, v218
	v_lshl_add_u64 v[216:217], v[114:115], 0, s[90:91]
	global_store_short v[216:217], v218, off
	v_add_f32_e32 v219, v51, v203
	s_add_u32 s90, s20, s13
	s_addc_u32 s91, s21, s15
	s_lshl_b64 s[90:91], s[90:91], 11
	v_cvt_pk_bf16_f32 v219, v219, v219
	v_lshl_add_u64 v[216:217], v[114:115], 0, s[90:91]
	global_store_short v[216:217], v219, off
	s_waitcnt lgkmcnt(1)
	v_add_f32_e32 v218, v52, v204
	s_add_u32 s90, s20, s22
	s_addc_u32 s91, s21, s23
	s_lshl_b64 s[90:91], s[90:91], 11
	v_cvt_pk_bf16_f32 v218, v218, v218
	v_lshl_add_u64 v[216:217], v[114:115], 0, s[90:91]
	global_store_short v[216:217], v218, off
	v_add_f32_e32 v219, v53, v205
	s_add_u32 s90, s20, s25
	s_addc_u32 s91, s21, s26
	s_lshl_b64 s[90:91], s[90:91], 11
	v_cvt_pk_bf16_f32 v219, v219, v219
	v_lshl_add_u64 v[216:217], v[114:115], 0, s[90:91]
	global_store_short v[216:217], v219, off
	s_waitcnt lgkmcnt(0)
	v_add_f32_e32 v218, v54, v206
	s_add_u32 s90, s20, s27
	s_addc_u32 s91, s21, s28
	s_lshl_b64 s[90:91], s[90:91], 11
	v_cvt_pk_bf16_f32 v218, v218, v218
	v_lshl_add_u64 v[216:217], v[114:115], 0, s[90:91]
	global_store_short v[216:217], v218, off
	v_add_f32_e32 v219, v55, v207
	s_add_u32 s90, s20, s29
	s_addc_u32 s91, s21, s30
	s_lshl_b64 s[90:91], s[90:91], 11
	v_cvt_pk_bf16_f32 v219, v219, v219
	v_lshl_add_u64 v[216:217], v[114:115], 0, s[90:91]
	global_store_short v[216:217], v219, off
	s_branch .LBB0_1164

.LBB0_1170:
	ds_read_b128 v[32:35], v139 offset:32768
	ds_read_b128 v[36:39], v139 offset:32800
	ds_read_b128 v[40:43], v139 offset:32896
	s_waitcnt lgkmcnt(2)
	v_pk_mul_f32 v[0:1], v[0:1], v[32:33]
	v_pk_mul_f32 v[2:3], v[2:3], v[34:35]
	ds_read_b128 v[32:35], v139 offset:32928
	s_waitcnt lgkmcnt(2)
	v_pk_mul_f32 v[4:5], v[4:5], v[36:37]
	v_pk_mul_f32 v[6:7], v[6:7], v[38:39]
	ds_read_b128 v[36:39], v139 offset:32960
	s_waitcnt lgkmcnt(1)
	v_pk_mul_f32 v[20:21], v[20:21], v[32:33]
	v_pk_mul_f32 v[22:23], v[22:23], v[34:35]
	ds_read_b128 v[32:35], v139 offset:32832
	v_pk_mul_f32 v[16:17], v[16:17], v[40:41]
	v_pk_mul_f32 v[18:19], v[18:19], v[42:43]
	s_waitcnt lgkmcnt(0)
	v_pk_mul_f32 v[8:9], v[8:9], v[32:33]
	v_pk_mul_f32 v[10:11], v[10:11], v[34:35]
	ds_read_b128 v[32:35], v139 offset:32864
	v_pk_mul_f32 v[24:25], v[24:25], v[36:37]
	v_pk_mul_f32 v[26:27], v[26:27], v[38:39]
	ds_read_b128 v[36:39], v139 offset:32992
	s_waitcnt lgkmcnt(1)
	v_pk_mul_f32 v[12:13], v[12:13], v[32:33]
	v_pk_mul_f32 v[14:15], v[14:15], v[34:35]
	s_waitcnt lgkmcnt(0)
	v_pk_mul_f32 v[28:29], v[28:29], v[36:37]
	v_pk_mul_f32 v[30:31], v[30:31], v[38:39]
	ds_read_b128 v[200:203], v148 offset:8704
	ds_read_b128 v[204:207], v149
	ds_read_b128 v[208:211], v149 offset:32
	ds_read_b128 v[212:215], v150 offset:8704
	ds_read_b128 v[216:219], v151 offset:8704
	ds_read_b128 v[194:197], v149 offset:64
	s_waitcnt lgkmcnt(4)
	v_mfma_f32_32x32x16_bf16 v[32:47], v[200:203], v[204:207], 0
	ds_read_b128 v[200:203], v152 offset:8704
	ds_read_b128 v[204:207], v149 offset:96
	s_waitcnt lgkmcnt(4)
	v_mfma_f32_32x32x16_bf16 v[32:47], v[212:215], v[208:211], v[32:47]
	ds_read_b128 v[208:211], v153 offset:8704
	ds_read_b128 v[212:215], v149 offset:128
	s_waitcnt lgkmcnt(4)
	v_mfma_f32_32x32x16_bf16 v[32:47], v[216:219], v[194:197], v[32:47]
	ds_read_b128 v[216:219], v154 offset:8704
	ds_read_b128 v[194:197], v149 offset:160
	s_waitcnt lgkmcnt(4)
	v_mfma_f32_32x32x16_bf16 v[32:47], v[200:203], v[204:207], v[32:47]
	ds_read_b128 v[200:203], v155 offset:8704
	ds_read_b128 v[204:207], v149 offset:192
	s_waitcnt lgkmcnt(4)
	v_mfma_f32_32x32x16_bf16 v[32:47], v[208:211], v[212:215], v[32:47]
	ds_read_b128 v[208:211], v156 offset:8704
	ds_read_b128 v[212:215], v149 offset:224
	s_waitcnt lgkmcnt(4)
	v_mfma_f32_32x32x16_bf16 v[32:47], v[216:219], v[194:197], v[32:47]
	s_waitcnt lgkmcnt(2)
	v_mfma_f32_32x32x16_bf16 v[32:47], v[200:203], v[204:207], v[32:47]
	s_waitcnt lgkmcnt(0)
	v_mfma_f32_32x32x16_bf16 v[32:47], v[208:211], v[212:215], v[32:47]
	s_nop 11
	v_cndmask_b32_e64 v48, v32, 0, s[36:37]
	v_cndmask_b32_e64 v167, v48, v32, s[40:41]
	v_cndmask_b32_e64 v168, 0, v33, s[40:41]
	v_cndmask_b32_e64 v169, v34, 0, s[42:43]
	v_cndmask_b32_e64 v170, v35, 0, s[44:45]
	v_cndmask_b32_e64 v171, v36, 0, s[46:47]
	v_cndmask_b32_e64 v172, v37, 0, s[48:49]
	v_cndmask_b32_e64 v173, v38, 0, s[50:51]
	v_cndmask_b32_e64 v174, v39, 0, s[52:53]
	ds_read2_b64 v[32:35], v142 offset1:2
	ds_read2_b64 v[36:39], v142 offset0:4 offset1:6
	v_cndmask_b32_e64 v175, v40, 0, s[54:55]
	v_cndmask_b32_e64 v193, v41, 0, s[56:57]
	v_cndmask_b32_e64 v194, v42, 0, s[58:59]
	v_cndmask_b32_e64 v195, v43, 0, s[60:61]
	v_cvt_pk_bf16_f32 v40, v0, v1
	v_cvt_pk_bf16_f32 v41, v2, v3
	v_cvt_pk_bf16_f32 v42, v4, v5
	v_cvt_pk_bf16_f32 v43, v6, v7
	v_cndmask_b32_e64 v44, v44, 0, s[62:63]
	v_cndmask_b32_e64 v45, v45, 0, s[64:65]
	s_waitcnt lgkmcnt(1)
	v_mfma_f32_32x32x16_bf16 v[48:63], v[32:35], v[40:43], 0
	ds_read2_b64 v[32:35], v142 offset0:8 offset1:10
	v_cvt_pk_bf16_f32 v40, v16, v17
	v_cvt_pk_bf16_f32 v41, v18, v19
	v_cvt_pk_bf16_f32 v42, v20, v21
	v_cvt_pk_bf16_f32 v43, v22, v23
	v_cndmask_b32_e64 v46, v46, 0, s[66:67]
	s_waitcnt lgkmcnt(0)
	v_mfma_f32_32x32x16_bf16 v[48:63], v[32:35], v[40:43], v[48:63]
	v_cvt_pk_bf16_f32 v32, v8, v9
	v_cvt_pk_bf16_f32 v33, v10, v11
	v_cvt_pk_bf16_f32 v34, v12, v13
	v_cvt_pk_bf16_f32 v35, v14, v15
	s_nop 1
	v_mfma_f32_32x32x16_bf16 v[48:63], v[36:39], v[32:35], v[48:63]
	ds_read2_b64 v[32:35], v142 offset0:12 offset1:14
	v_cvt_pk_bf16_f32 v36, v24, v25
	v_cvt_pk_bf16_f32 v37, v26, v27
	v_cvt_pk_bf16_f32 v38, v28, v29
	v_cvt_pk_bf16_f32 v39, v30, v31
	s_waitcnt lgkmcnt(0)
	s_nop 0
	v_mfma_f32_32x32x16_bf16 v[48:63], v[32:35], v[36:39], v[48:63]
	v_cndmask_b32_e64 v32, v47, 0, s[68:69]
	v_cvt_pk_bf16_f32 v36, v167, v168
	v_cvt_pk_bf16_f32 v33, v169, v170
	v_cvt_pk_bf16_f32 v34, v171, v172
	v_cvt_pk_bf16_f32 v35, v173, v174
	v_cvt_pk_bf16_f32 v37, v175, v193
	v_cvt_pk_bf16_f32 v38, v194, v195
	v_cvt_pk_bf16_f32 v39, v44, v45
	v_cvt_pk_bf16_f32 v32, v46, v32
	v_cndmask_b32_e64 v35, v32, v35, s[70:71]
	v_cndmask_b32_e64 v34, v39, v34, s[70:71]
	v_cndmask_b32_e64 v33, v38, v33, s[70:71]
	v_cndmask_b32_e64 v32, v37, v36, s[70:71]
	ds_read_b64_tr_b16 v[36:37], v124
	ds_read_b64_tr_b16 v[38:39], v125
	s_waitcnt lgkmcnt(0)
	s_nop 1
	v_mfma_f32_32x32x16_bf16 v[48:63], v[32:35], v[36:39], v[48:63]
	s_mov_b64 s[10:11], exec
	s_cmp_lg_u64 s[72:73], 0
	s_cbranch_scc0 .Lsov1_k0
	s_nop 9
	ds_write2_b32 v166, v48, v49 offset0:128 offset1:160
	ds_write2_b32 v166, v50, v51 offset0:192 offset1:224
	ds_write2_b32 v165, v52, v53 offset0:128 offset1:160
	ds_write2_b32 v165, v54, v55 offset0:192 offset1:224
	s_branch .LBB0_1172
.Lsov1_k0:
	s_nop 9
	ds_write2_b32 v164, v56, v57 offset0:128 offset1:160
	ds_write2_b32 v164, v58, v59 offset0:192 offset1:224
	ds_write2_b32 v163, v60, v61 offset0:128 offset1:160
	ds_write2_b32 v163, v62, v63 offset0:192 offset1:224
.LBB0_1172:
	s_or_b64 exec, exec, s[10:11]
	ds_read_b64_tr_b16 v[168:169], v126
	ds_read_b64_tr_b16 v[170:171], v127
	ds_read_b64_tr_b16 v[164:165], v128
	ds_read_b64_tr_b16 v[166:167], v129
	ds_read_b64_tr_b16 v[44:45], v130
	ds_read_b64_tr_b16 v[46:47], v131
	ds_read_b64_tr_b16 v[40:41], v132
	ds_read_b64_tr_b16 v[42:43], v133
	ds_read_b64_tr_b16 v[36:37], v120
	ds_read_b64_tr_b16 v[38:39], v121
	ds_read_b64_tr_b16 v[32:33], v122
	ds_read_b64_tr_b16 v[34:35], v123
	s_waitcnt lgkmcnt(0)
	s_waitcnt lgkmcnt(0)
	v_mfma_f32_32x32x16_bf16 v[0:15], v[168:171], v[36:39], v[0:15]
	s_barrier
	v_mfma_f32_32x32x16_bf16 v[16:31], v[44:47], v[36:39], v[16:31]
	v_mfma_f32_32x32x16_bf16 v[0:15], v[164:167], v[32:35], v[0:15]
	v_mfma_f32_32x32x16_bf16 v[16:31], v[40:43], v[32:35], v[16:31]
	s_mov_b64 s[10:11], exec
	s_cmp_lg_u64 s[70:71], 0
	s_cbranch_scc1 .Lsot1_k0
	s_cmp_lg_u64 s[72:73], 0
	s_cbranch_scc0 .LBB0_1153
	s_sub_i32 s20, s2, 32
	s_add_i32 s21, s3, 64
	s_and_b64 s[18:19], s[74:75], exec
	s_cselect_b32 s18, s20, s21
	s_ashr_i32 s19, s18, 31
	s_add_u32 s18, s18, s16
	s_addc_u32 s19, s19, s24
	v_add_u32_e32 v194, 0x8800, v143
	ds_read2_b32 v[208:209], v194 offset0:128 offset1:160
	ds_read2_b32 v[210:211], v194 offset0:192 offset1:224
	v_add_u32_e32 v195, 0x8c00, v143
	ds_read2_b32 v[212:213], v195 offset0:128 offset1:160
	ds_read2_b32 v[214:215], v195 offset0:192 offset1:224
	s_waitcnt lgkmcnt(3)
	v_add_f32_e32 v218, v56, v208
	s_add_u32 s20, s18, s31
	s_addc_u32 s21, s19, s33
	s_lshl_b64 s[20:21], s[20:21], 11
	v_cvt_pk_bf16_f32 v218, v218, v218
	v_lshl_add_u64 v[216:217], v[114:115], 0, s[20:21]
	global_store_short v[216:217], v218, off
	v_add_f32_e32 v219, v57, v209
	s_add_u32 s20, s18, s34
	s_addc_u32 s21, s19, s35
	s_lshl_b64 s[20:21], s[20:21], 11
	v_cvt_pk_bf16_f32 v219, v219, v219
	v_lshl_add_u64 v[216:217], v[114:115], 0, s[20:21]
	global_store_short v[216:217], v219, off
	s_waitcnt lgkmcnt(2)
	v_add_f32_e32 v218, v58, v210
	s_add_u32 s20, s18, s38
	s_addc_u32 s21, s19, s39
	s_lshl_b64 s[20:21], s[20:21], 11
	v_cvt_pk_bf16_f32 v218, v218, v218
	v_lshl_add_u64 v[216:217], v[114:115], 0, s[20:21]
	global_store_short v[216:217], v218, off
	v_add_f32_e32 v219, v59, v211
	s_add_u32 s20, s18, s77
	s_addc_u32 s21, s19, s78
	s_lshl_b64 s[20:21], s[20:21], 11
	v_cvt_pk_bf16_f32 v219, v219, v219
	v_lshl_add_u64 v[216:217], v[114:115], 0, s[20:21]
	global_store_short v[216:217], v219, off
	s_waitcnt lgkmcnt(1)
	v_add_f32_e32 v218, v60, v212
	s_add_u32 s20, s18, s79
	s_addc_u32 s21, s19, s80
	s_lshl_b64 s[20:21], s[20:21], 11
	v_cvt_pk_bf16_f32 v218, v218, v218
	v_lshl_add_u64 v[216:217], v[114:115], 0, s[20:21]
	global_store_short v[216:217], v218, off
	v_add_f32_e32 v219, v61, v213
	s_add_u32 s20, s18, s81
	s_addc_u32 s21, s19, s82
	s_lshl_b64 s[20:21], s[20:21], 11
	v_cvt_pk_bf16_f32 v219, v219, v219
	v_lshl_add_u64 v[216:217], v[114:115], 0, s[20:21]
	global_store_short v[216:217], v219, off
	s_waitcnt lgkmcnt(0)
	v_add_f32_e32 v218, v62, v214
	s_add_u32 s20, s18, s83
	s_addc_u32 s21, s19, s84
	s_lshl_b64 s[20:21], s[20:21], 11
	v_cvt_pk_bf16_f32 v218, v218, v218
	v_lshl_add_u64 v[216:217], v[114:115], 0, s[20:21]
	global_store_short v[216:217], v218, off
	v_add_f32_e32 v219, v63, v215
	s_add_u32 s20, s18, s86
	s_addc_u32 s21, s19, s87
	s_lshl_b64 s[20:21], s[20:21], 11
	v_cvt_pk_bf16_f32 v219, v219, v219
	v_lshl_add_u64 v[216:217], v[114:115], 0, s[20:21]
	global_store_short v[216:217], v219, off
	s_branch .LBB0_1153
.Lsot1_k0:
	s_sub_i32 s20, s2, 32
	s_add_i32 s21, s3, 64
	s_and_b64 s[18:19], s[74:75], exec
	s_cselect_b32 s18, s20, s21
	s_ashr_i32 s19, s18, 31
	s_add_u32 s18, s18, s16
	s_addc_u32 s19, s19, s24
	ds_read2_b32 v[200:201], v162 offset0:128 offset1:160
	ds_read2_b32 v[202:203], v162 offset0:192 offset1:224
	ds_read2_b32 v[204:205], v161 offset0:128 offset1:160
	ds_read2_b32 v[206:207], v161 offset0:192 offset1:224
	s_waitcnt lgkmcnt(3)
	v_add_f32_e32 v218, v48, v200
	s_lshl_b64 s[20:21], s[18:19], 11
	v_cvt_pk_bf16_f32 v218, v218, v218
	v_lshl_add_u64 v[216:217], v[114:115], 0, s[20:21]
	global_store_short v[216:217], v218, off
	v_add_f32_e32 v219, v49, v201
	s_add_u32 s20, s18, s5
	s_addc_u32 s21, s19, s6
	s_lshl_b64 s[20:21], s[20:21], 11
	v_cvt_pk_bf16_f32 v219, v219, v219
	v_lshl_add_u64 v[216:217], v[114:115], 0, s[20:21]
	global_store_short v[216:217], v219, off
	s_waitcnt lgkmcnt(2)
	v_add_f32_e32 v218, v50, v202
	s_add_u32 s20, s18, s7
	s_addc_u32 s21, s19, s12
	s_lshl_b64 s[20:21], s[20:21], 11
	v_cvt_pk_bf16_f32 v218, v218, v218
	v_lshl_add_u64 v[216:217], v[114:115], 0, s[20:21]
	global_store_short v[216:217], v218, off
	v_add_f32_e32 v219, v51, v203
	s_add_u32 s20, s18, s13
	s_addc_u32 s21, s19, s15
	s_lshl_b64 s[20:21], s[20:21], 11
	v_cvt_pk_bf16_f32 v219, v219, v219
	v_lshl_add_u64 v[216:217], v[114:115], 0, s[20:21]
	global_store_short v[216:217], v219, off
	s_waitcnt lgkmcnt(1)
	v_add_f32_e32 v218, v52, v204
	s_add_u32 s20, s18, s22
	s_addc_u32 s21, s19, s23
	s_lshl_b64 s[20:21], s[20:21], 11
	v_cvt_pk_bf16_f32 v218, v218, v218
	v_lshl_add_u64 v[216:217], v[114:115], 0, s[20:21]
	global_store_short v[216:217], v218, off
	v_add_f32_e32 v219, v53, v205
	s_add_u32 s20, s18, s25
	s_addc_u32 s21, s19, s26
	s_lshl_b64 s[20:21], s[20:21], 11
	v_cvt_pk_bf16_f32 v219, v219, v219
	v_lshl_add_u64 v[216:217], v[114:115], 0, s[20:21]
	global_store_short v[216:217], v219, off
	s_waitcnt lgkmcnt(0)
	v_add_f32_e32 v218, v54, v206
	s_add_u32 s20, s18, s27
	s_addc_u32 s21, s19, s28
	s_lshl_b64 s[20:21], s[20:21], 11
	v_cvt_pk_bf16_f32 v218, v218, v218
	v_lshl_add_u64 v[216:217], v[114:115], 0, s[20:21]
	global_store_short v[216:217], v218, off
	v_add_f32_e32 v219, v55, v207
	s_add_u32 s20, s18, s29
	s_addc_u32 s21, s19, s30
	s_lshl_b64 s[20:21], s[20:21], 11
	v_cvt_pk_bf16_f32 v219, v219, v219
	v_lshl_add_u64 v[216:217], v[114:115], 0, s[20:21]
	global_store_short v[216:217], v219, off
	s_branch .LBB0_1153
